# in-proj epilogue (rope rows): one vmcnt(0) before the first row instead of a counted wait per row; redundant lgkmcnt waits and doubled nops removed from the norm DPP reduction
# speedup vs baseline: 1.0013x; 1.0013x over previous
.LBB0_305:
	s_and_b64 vcc, exec, s[6:7]
	s_cbranch_vccz .LBB0_444
	v_or_b32_e32 v206, 1, v64
	v_lshlrev_b32_e32 v65, 5, v64
	s_mov_b32 s6, 0x1f980
	v_lshlrev_b32_e32 v70, 5, v206
	v_and_or_b32 v65, v65, s6, v108
	v_and_or_b32 v70, v70, s41, v108
	v_readlane_b32 s56, v250, 24
	v_lshlrev_b32_e32 v65, 3, v65
	v_lshlrev_b32_e32 v70, 3, v70
	v_readlane_b32 s70, v250, 38
	v_readlane_b32 s71, v250, 39
	v_or_b32_e32 v198, 2, v64
	v_or_b32_e32 v192, 3, v64
	s_nop 2
	global_load_dwordx2 v[208:209], v65, s[70:71]
	global_load_dwordx2 v[204:205], v65, s[70:71] offset:128
	global_load_dwordx2 v[86:87], v70, s[70:71]
	global_load_dwordx2 v[84:85], v70, s[70:71] offset:128
	v_lshlrev_b32_e32 v65, 5, v198
	v_lshlrev_b32_e32 v70, 5, v192
	v_and_or_b32 v65, v65, s42, v108
	v_and_or_b32 v70, v70, s43, v108
	v_lshlrev_b32_e32 v65, 3, v65
	v_lshlrev_b32_e32 v70, 3, v70
	v_or_b32_e32 v186, 16, v64
	v_or_b32_e32 v180, 17, v64
	global_load_dwordx2 v[202:203], v65, s[70:71]
	global_load_dwordx2 v[200:201], v65, s[70:71] offset:128
	global_load_dwordx2 v[196:197], v70, s[70:71]
	global_load_dwordx2 v[194:195], v70, s[70:71] offset:128
	v_lshlrev_b32_e32 v65, 5, v186
	v_lshlrev_b32_e32 v70, 5, v180
	v_and_or_b32 v65, v65, s44, v108
	v_and_or_b32 v70, v70, s41, v108
	v_lshlrev_b32_e32 v65, 3, v65
	v_lshlrev_b32_e32 v70, 3, v70
	v_or_b32_e32 v174, 18, v64
	v_or_b32_e32 v168, 19, v64
	global_load_dwordx2 v[190:191], v65, s[70:71]
	global_load_dwordx2 v[188:189], v65, s[70:71] offset:128
	global_load_dwordx2 v[184:185], v70, s[70:71]
	global_load_dwordx2 v[182:183], v70, s[70:71] offset:128
	v_lshlrev_b32_e32 v65, 5, v174
	v_lshlrev_b32_e32 v70, 5, v168
	v_and_or_b32 v65, v65, s42, v108
	v_and_or_b32 v70, v70, s43, v108
	v_lshlrev_b32_e32 v65, 3, v65
	v_lshlrev_b32_e32 v70, 3, v70
	v_or_b32_e32 v162, 32, v64
	v_or_b32_e32 v156, 33, v64
	global_load_dwordx2 v[178:179], v65, s[70:71]
	global_load_dwordx2 v[176:177], v65, s[70:71] offset:128
	global_load_dwordx2 v[172:173], v70, s[70:71]
	global_load_dwordx2 v[170:171], v70, s[70:71] offset:128
	v_lshlrev_b32_e32 v65, 5, v162
	v_lshlrev_b32_e32 v70, 5, v156
	v_and_or_b32 v65, v65, s44, v108
	v_and_or_b32 v70, v70, s41, v108
	v_lshlrev_b32_e32 v65, 3, v65
	v_lshlrev_b32_e32 v70, 3, v70
	v_or_b32_e32 v150, 34, v64
	v_or_b32_e32 v144, 35, v64
	global_load_dwordx2 v[166:167], v65, s[70:71]
	global_load_dwordx2 v[164:165], v65, s[70:71] offset:128
	global_load_dwordx2 v[160:161], v70, s[70:71]
	global_load_dwordx2 v[158:159], v70, s[70:71] offset:128
	v_lshlrev_b32_e32 v65, 5, v150
	v_lshlrev_b32_e32 v70, 5, v144
	v_and_or_b32 v65, v65, s42, v108
	v_and_or_b32 v70, v70, s43, v108
	v_lshlrev_b32_e32 v65, 3, v65
	v_lshlrev_b32_e32 v70, 3, v70
	s_waitcnt vmcnt(20)
	v_or_b32_e32 v94, 48, v64
	v_or_b32_e32 v88, 49, v64
	global_load_dwordx2 v[154:155], v65, s[70:71]
	global_load_dwordx2 v[152:153], v65, s[70:71] offset:128
	global_load_dwordx2 v[148:149], v70, s[70:71]
	global_load_dwordx2 v[146:147], v70, s[70:71] offset:128
	v_lshlrev_b32_e32 v65, 5, v94
	v_lshlrev_b32_e32 v70, 5, v88
	v_and_or_b32 v65, v65, s44, v108
	v_and_or_b32 v70, v70, s41, v108
	v_lshlrev_b32_e32 v65, 3, v65
	v_lshlrev_b32_e32 v70, 3, v70
	v_or_b32_e32 v78, 50, v64
	global_load_dwordx2 v[142:143], v65, s[70:71]
	global_load_dwordx2 v[140:141], v65, s[70:71] offset:128
	global_load_dwordx2 v[92:93], v70, s[70:71]
	global_load_dwordx2 v[90:91], v70, s[70:71] offset:128
	v_lshlrev_b32_e32 v65, 5, v78
	v_or_b32_e32 v70, 51, v64
	v_and_or_b32 v65, v65, s42, v108
	v_lshlrev_b32_e32 v71, 5, v70
	v_lshlrev_b32_e32 v65, 3, v65
	v_and_or_b32 v71, v71, s43, v108
	v_lshlrev_b32_e32 v71, 3, v71
	global_load_dwordx2 v[82:83], v65, s[70:71]
	global_load_dwordx2 v[80:81], v65, s[70:71] offset:128
	global_load_dwordx2 v[74:75], v71, s[70:71]
	global_load_dwordx2 v[72:73], v71, s[70:71] offset:128
	s_and_b64 vcc, exec, s[4:5]
	v_readlane_b32 s57, v250, 25
	v_readlane_b32 s58, v250, 26
	v_readlane_b32 s59, v250, 27
	v_readlane_b32 s60, v250, 28
	v_readlane_b32 s61, v250, 29
	v_readlane_b32 s62, v250, 30
	v_readlane_b32 s63, v250, 31
	v_readlane_b32 s64, v250, 32
	v_readlane_b32 s65, v250, 33
	v_readlane_b32 s66, v250, 34
	v_readlane_b32 s67, v250, 35
	v_readlane_b32 s68, v250, 36
	v_readlane_b32 s69, v250, 37
	s_cbranch_vccnz .LBB0_334
	v_mov_b32_e32 v76, v44
	v_mov_b32_e32 v77, v52
	v_and_b32_e32 v79, 64, v121
	v_pk_mul_f32 v[210:211], v[76:77], v[76:77]
	v_mov_b32_e32 v212, v56
	v_mov_b32_e32 v213, v60
	v_add_u32_e32 v79, 64, v79
	v_pk_mul_f32 v[212:213], v[212:213], v[212:213]
	v_add_f32_e32 v65, v210, v211
	v_add_f32_e32 v65, v213, v65
	v_add_f32_e32 v65, v212, v65
	s_nop 1
	v_add_f32_dpp v65, v65, v65 quad_perm:[1,0,3,2] row_mask:0xf bank_mask:0xf
	s_nop 1
	v_add_f32_dpp v65, v65, v65 quad_perm:[2,3,0,1] row_mask:0xf bank_mask:0xf
	s_nop 1
	v_add_f32_dpp v65, v65, v65 row_half_mirror row_mask:0xf bank_mask:0xf
	s_nop 1
	v_add_f32_dpp v65, v65, v65 row_mirror row_mask:0xf bank_mask:0xf
	v_fmamk_f32 v65, v65, 0x3c800000, v113
	v_mul_f32_e32 v71, 0x4b800000, v65
	v_cmp_gt_f32_e32 vcc, s45, v65
	s_nop 1
	v_cndmask_b32_e32 v65, v65, v71, vcc
	v_rsq_f32_e32 v65, v65
	s_nop 0
	v_mul_f32_e32 v71, 0x45800000, v65
	v_cndmask_b32_e32 v100, v65, v71, vcc
	v_pk_mul_f32 v[76:77], v[76:77], v[100:101] op_sel_hi:[1,0]
	s_nop 0
	v_pk_mul_f32 v[210:211], v[66:67], v[76:77]
	v_mov_b32_e32 v76, v60
	v_mov_b32_e32 v77, v56
	v_pk_mul_f32 v[76:77], v[76:77], v[100:101] op_sel_hi:[1,0]
	s_nop 0
	v_pk_mul_f32 v[212:213], v[68:69], v[76:77]
	s_branch .LBB0_335

.LBB0_335:
	s_waitcnt vmcnt(0)
	v_mul_f32_e32 v65, v209, v212
	v_fma_f32 v65, v208, v210, -v65
	v_mul_f32_e32 v79, s51, v65
	v_mul_f32_e32 v65, v209, v210
	v_fmac_f32_e32 v65, v208, v212
	v_mul_f32_e32 v71, s51, v65
	v_mul_f32_e32 v65, v205, v213
	v_fma_f32 v65, v204, v211, -v65
	s_cmpk_lg_i32 s52, 0xb00
	v_mul_f32_e32 v95, s51, v65
	v_mul_f32_e32 v65, v205, v211
	s_cselect_b64 s[8:9], -1, 0
	s_lshl_b32 s12, s52, 15
	v_fmac_f32_e32 v65, v204, v213
	v_lshl_add_u64 v[76:77], v[132:133], 0, s[12:13]
	v_mul_f32_e32 v89, s51, v65
	s_mov_b64 s[6:7], -1
	s_and_b64 vcc, exec, s[8:9]
	s_cbranch_vccz .LBB0_339
	v_ashrrev_i32_e32 v65, 31, v64
	v_lshlrev_b64 v[204:205], 7, v[64:65]
	v_lshl_add_u64 v[204:205], v[76:77], 0, v[204:205]
	v_cvt_pk_bf16_f32 v65, v79, v101
	global_store_short v[204:205], v65, off
	v_cvt_pk_bf16_f32 v65, v95, v101
	global_store_short v[204:205], v65, off offset:32
	v_cvt_pk_bf16_f32 v65, v71, v101
	global_store_short v[204:205], v65, off offset:64
	v_cvt_pk_bf16_f32 v65, v89, v101
	global_store_short v[204:205], v65, off offset:96
	v_ashrrev_i32_e32 v204, 4, v64
	v_ashrrev_i32_e32 v205, 31, v204
	s_cbranch_execz .LBB0_340

.LBB0_338:
	v_mov_b32_e32 v100, v61
	v_and_b32_e32 v79, 64, v121
	v_pk_mul_f32 v[210:211], v[208:209], v[208:209]
	v_pk_mov_b32 v[212:213], v[56:57], v[100:101] op_sel:[1,0]
	v_add_u32_e32 v79, 64, v79
	v_pk_mul_f32 v[212:213], v[212:213], v[212:213]
	v_add_f32_e32 v65, v210, v211
	v_add_f32_e32 v65, v213, v65
	v_add_f32_e32 v65, v212, v65
	s_nop 1
	v_add_f32_dpp v65, v65, v65 quad_perm:[1,0,3,2] row_mask:0xf bank_mask:0xf
	v_mov_b32_e32 v210, v61
	v_mov_b32_e32 v211, v57
	s_nop 1
	v_add_f32_dpp v65, v65, v65 quad_perm:[2,3,0,1] row_mask:0xf bank_mask:0xf
	s_nop 1
	v_add_f32_dpp v65, v65, v65 row_half_mirror row_mask:0xf bank_mask:0xf
	s_nop 1
	v_add_f32_dpp v65, v65, v65 row_mirror row_mask:0xf bank_mask:0xf
	v_fmamk_f32 v65, v65, 0x3c800000, v113
	v_mul_f32_e32 v71, 0x4b800000, v65
	v_cmp_gt_f32_e32 vcc, s45, v65
	s_nop 1
	v_cndmask_b32_e32 v65, v65, v71, vcc
	v_rsq_f32_e32 v65, v65
	s_nop 0
	v_mul_f32_e32 v71, 0x45800000, v65
	v_cndmask_b32_e32 v100, v65, v71, vcc
	v_pk_mul_f32 v[208:209], v[208:209], v[100:101] op_sel_hi:[1,0]
	v_pk_mul_f32 v[210:211], v[210:211], v[100:101] op_sel_hi:[1,0]
	v_pk_mul_f32 v[208:209], v[66:67], v[208:209]
	v_pk_mul_f32 v[210:211], v[68:69], v[210:211]
	s_branch .LBB0_342

.LBB0_342:
	v_mul_f32_e32 v65, v87, v210
	v_mul_f32_e32 v79, v85, v211
	v_fma_f32 v65, v86, v208, -v65
	v_fma_f32 v79, v84, v209, -v79
	v_mul_f32_e32 v71, s51, v65
	v_mul_f32_e32 v65, v87, v208
	v_mul_f32_e32 v89, s51, v79
	v_mul_f32_e32 v79, v85, v209
	v_fmac_f32_e32 v65, v86, v210
	v_fmac_f32_e32 v79, v84, v211
	v_cndmask_b32_e64 v84, 0, 1, s[8:9]
	v_mul_f32_e32 v65, s51, v65
	v_mul_f32_e32 v79, s51, v79
	v_cmp_ne_u32_e64 s[6:7], 1, v84
	s_andn2_b64 vcc, exec, s[8:9]
	s_mov_b64 s[8:9], -1
	s_cbranch_vccnz .LBB0_346
	v_ashrrev_i32_e32 v207, 31, v206
	v_lshlrev_b64 v[84:85], 7, v[206:207]
	v_lshl_add_u64 v[84:85], v[76:77], 0, v[84:85]
	v_cvt_pk_bf16_f32 v86, v71, v101
	global_store_short v[84:85], v86, off
	v_cvt_pk_bf16_f32 v86, v89, v101
	global_store_short v[84:85], v86, off offset:32
	v_cvt_pk_bf16_f32 v86, v65, v101
	global_store_short v[84:85], v86, off offset:64
	v_cvt_pk_bf16_f32 v86, v79, v101
	global_store_short v[84:85], v86, off offset:96
	v_lshlrev_b32_e32 v86, 1, v102
	v_lshlrev_b32_e32 v84, 1, v114
	s_cbranch_execz .LBB0_347

.LBB0_345:
	v_and_b32_e32 v79, 64, v121
	v_pk_mul_f32 v[208:209], v[206:207], v[206:207]
	v_mov_b32_e32 v210, v58
	v_mov_b32_e32 v211, v62
	v_add_u32_e32 v79, 64, v79
	v_pk_mul_f32 v[210:211], v[210:211], v[210:211]
	v_add_f32_e32 v65, v208, v209
	v_add_f32_e32 v65, v211, v65
	v_add_f32_e32 v65, v210, v65
	s_nop 1
	v_add_f32_dpp v65, v65, v65 quad_perm:[1,0,3,2] row_mask:0xf bank_mask:0xf
	v_mov_b32_e32 v208, v62
	v_mov_b32_e32 v209, v58
	s_nop 1
	v_add_f32_dpp v65, v65, v65 quad_perm:[2,3,0,1] row_mask:0xf bank_mask:0xf
	s_nop 1
	v_add_f32_dpp v65, v65, v65 row_half_mirror row_mask:0xf bank_mask:0xf
	s_nop 1
	v_add_f32_dpp v65, v65, v65 row_mirror row_mask:0xf bank_mask:0xf
	v_fmamk_f32 v65, v65, 0x3c800000, v113
	v_mul_f32_e32 v71, 0x4b800000, v65
	v_cmp_gt_f32_e32 vcc, s45, v65
	s_nop 1
	v_cndmask_b32_e32 v65, v65, v71, vcc
	v_rsq_f32_e32 v65, v65
	s_nop 0
	v_mul_f32_e32 v71, 0x45800000, v65
	v_cndmask_b32_e32 v100, v65, v71, vcc
	v_pk_mul_f32 v[206:207], v[206:207], v[100:101] op_sel_hi:[1,0]
	v_pk_mul_f32 v[208:209], v[208:209], v[100:101] op_sel_hi:[1,0]
	v_pk_mul_f32 v[206:207], v[66:67], v[206:207]
	v_pk_mul_f32 v[208:209], v[68:69], v[208:209]
	s_branch .LBB0_349

.LBB0_349:
	v_mul_f32_e32 v65, v203, v208
	v_mul_f32_e32 v79, v201, v209
	v_fma_f32 v65, v202, v206, -v65
	v_fma_f32 v79, v200, v207, -v79
	v_mul_f32_e32 v71, s51, v65
	v_mul_f32_e32 v65, v203, v206
	v_mul_f32_e32 v89, s51, v79
	v_mul_f32_e32 v79, v201, v207
	v_fmac_f32_e32 v65, v202, v208
	v_fmac_f32_e32 v79, v200, v209
	v_mul_f32_e32 v65, s51, v65
	v_mul_f32_e32 v79, s51, v79
	s_and_b64 vcc, exec, s[6:7]
	s_mov_b64 s[8:9], -1
	s_cbranch_vccnz .LBB0_353
	v_ashrrev_i32_e32 v199, 31, v198
	v_lshlrev_b64 v[200:201], 7, v[198:199]
	v_lshl_add_u64 v[200:201], v[76:77], 0, v[200:201]
	v_cvt_pk_bf16_f32 v85, v71, v101
	global_store_short v[200:201], v85, off
	v_cvt_pk_bf16_f32 v85, v89, v101
	global_store_short v[200:201], v85, off offset:32
	v_cvt_pk_bf16_f32 v85, v65, v101
	global_store_short v[200:201], v85, off offset:64
	v_cvt_pk_bf16_f32 v85, v79, v101
	global_store_short v[200:201], v85, off offset:96
	s_cbranch_execz .LBB0_354

.LBB0_352:
	v_mov_b32_e32 v100, v63
	v_and_b32_e32 v79, 64, v121
	v_pk_mul_f32 v[200:201], v[198:199], v[198:199]
	v_pk_mov_b32 v[202:203], v[58:59], v[100:101] op_sel:[1,0]
	v_add_u32_e32 v79, 64, v79
	v_pk_mul_f32 v[202:203], v[202:203], v[202:203]
	v_add_f32_e32 v65, v200, v201
	v_add_f32_e32 v65, v203, v65
	v_add_f32_e32 v65, v202, v65
	s_nop 1
	v_add_f32_dpp v65, v65, v65 quad_perm:[1,0,3,2] row_mask:0xf bank_mask:0xf
	v_mov_b32_e32 v200, v63
	v_mov_b32_e32 v201, v59
	s_nop 1
	v_add_f32_dpp v65, v65, v65 quad_perm:[2,3,0,1] row_mask:0xf bank_mask:0xf
	s_nop 1
	v_add_f32_dpp v65, v65, v65 row_half_mirror row_mask:0xf bank_mask:0xf
	s_nop 1
	v_add_f32_dpp v65, v65, v65 row_mirror row_mask:0xf bank_mask:0xf
	v_fmamk_f32 v65, v65, 0x3c800000, v113
	v_mul_f32_e32 v71, 0x4b800000, v65
	v_cmp_gt_f32_e32 vcc, s45, v65
	s_nop 1
	v_cndmask_b32_e32 v65, v65, v71, vcc
	v_rsq_f32_e32 v65, v65
	s_nop 0
	v_mul_f32_e32 v71, 0x45800000, v65
	v_cndmask_b32_e32 v100, v65, v71, vcc
	v_pk_mul_f32 v[198:199], v[198:199], v[100:101] op_sel_hi:[1,0]
	v_pk_mul_f32 v[200:201], v[200:201], v[100:101] op_sel_hi:[1,0]
	v_pk_mul_f32 v[198:199], v[66:67], v[198:199]
	v_pk_mul_f32 v[200:201], v[68:69], v[200:201]
	s_branch .LBB0_356

.LBB0_356:
	v_mul_f32_e32 v65, v197, v200
	v_mul_f32_e32 v79, v195, v201
	v_fma_f32 v65, v196, v198, -v65
	v_fma_f32 v79, v194, v199, -v79
	v_mul_f32_e32 v71, s51, v65
	v_mul_f32_e32 v65, v197, v198
	v_mul_f32_e32 v89, s51, v79
	v_mul_f32_e32 v79, v195, v199
	v_fmac_f32_e32 v65, v196, v200
	v_fmac_f32_e32 v79, v194, v201
	v_mul_f32_e32 v65, s51, v65
	v_mul_f32_e32 v79, s51, v79
	s_and_b64 vcc, exec, s[6:7]
	s_mov_b64 s[8:9], -1
	s_cbranch_vccnz .LBB0_360
	v_ashrrev_i32_e32 v193, 31, v192
	v_lshlrev_b64 v[194:195], 7, v[192:193]
	v_lshl_add_u64 v[194:195], v[76:77], 0, v[194:195]
	v_cvt_pk_bf16_f32 v85, v71, v101
	global_store_short v[194:195], v85, off
	v_cvt_pk_bf16_f32 v85, v89, v101
	global_store_short v[194:195], v85, off offset:32
	v_cvt_pk_bf16_f32 v85, v65, v101
	global_store_short v[194:195], v85, off offset:64
	v_cvt_pk_bf16_f32 v85, v79, v101
	global_store_short v[194:195], v85, off offset:96
	s_cbranch_execz .LBB0_361

.LBB0_359:
	v_and_b32_e32 v79, 64, v121
	v_pk_mul_f32 v[194:195], v[192:193], v[192:193]
	v_mov_b32_e32 v196, v28
	v_mov_b32_e32 v197, v32
	v_add_u32_e32 v79, 64, v79
	v_pk_mul_f32 v[196:197], v[196:197], v[196:197]
	v_add_f32_e32 v65, v194, v195
	v_add_f32_e32 v65, v197, v65
	v_add_f32_e32 v65, v196, v65
	s_nop 1
	v_add_f32_dpp v65, v65, v65 quad_perm:[1,0,3,2] row_mask:0xf bank_mask:0xf
	v_mov_b32_e32 v194, v32
	v_mov_b32_e32 v195, v28
	s_nop 1
	v_add_f32_dpp v65, v65, v65 quad_perm:[2,3,0,1] row_mask:0xf bank_mask:0xf
	s_nop 1
	v_add_f32_dpp v65, v65, v65 row_half_mirror row_mask:0xf bank_mask:0xf
	s_nop 1
	v_add_f32_dpp v65, v65, v65 row_mirror row_mask:0xf bank_mask:0xf
	v_fmamk_f32 v65, v65, 0x3c800000, v113
	v_mul_f32_e32 v71, 0x4b800000, v65
	v_cmp_gt_f32_e32 vcc, s45, v65
	s_nop 1
	v_cndmask_b32_e32 v65, v65, v71, vcc
	v_rsq_f32_e32 v65, v65
	s_nop 0
	v_mul_f32_e32 v71, 0x45800000, v65
	v_cndmask_b32_e32 v100, v65, v71, vcc
	v_pk_mul_f32 v[192:193], v[192:193], v[100:101] op_sel_hi:[1,0]
	v_pk_mul_f32 v[194:195], v[194:195], v[100:101] op_sel_hi:[1,0]
	v_pk_mul_f32 v[192:193], v[66:67], v[192:193]
	v_pk_mul_f32 v[194:195], v[68:69], v[194:195]
	s_branch .LBB0_363

.LBB0_363:
	v_mul_f32_e32 v65, v191, v194
	v_mul_f32_e32 v79, v189, v195
	v_fma_f32 v65, v190, v192, -v65
	v_fma_f32 v79, v188, v193, -v79
	v_mul_f32_e32 v71, s51, v65
	v_mul_f32_e32 v65, v191, v192
	v_mul_f32_e32 v85, s51, v79
	v_mul_f32_e32 v79, v189, v193
	v_fmac_f32_e32 v65, v190, v194
	v_fmac_f32_e32 v79, v188, v195
	v_mul_f32_e32 v65, s51, v65
	v_mul_f32_e32 v79, s51, v79
	s_and_b64 vcc, exec, s[6:7]
	s_mov_b64 s[8:9], -1
	s_cbranch_vccnz .LBB0_367
	v_ashrrev_i32_e32 v187, 31, v186
	v_lshlrev_b64 v[188:189], 7, v[186:187]
	v_lshl_add_u64 v[188:189], v[76:77], 0, v[188:189]
	v_cvt_pk_bf16_f32 v87, v71, v101
	global_store_short v[188:189], v87, off
	v_cvt_pk_bf16_f32 v87, v85, v101
	global_store_short v[188:189], v87, off offset:32
	v_cvt_pk_bf16_f32 v87, v65, v101
	global_store_short v[188:189], v87, off offset:64
	v_cvt_pk_bf16_f32 v87, v79, v101
	global_store_short v[188:189], v87, off offset:96
	s_cbranch_execz .LBB0_368

.LBB0_366:
	v_mov_b32_e32 v100, v33
	v_and_b32_e32 v79, 64, v121
	v_pk_mul_f32 v[188:189], v[186:187], v[186:187]
	v_pk_mov_b32 v[190:191], v[28:29], v[100:101] op_sel:[1,0]
	v_add_u32_e32 v79, 64, v79
	v_pk_mul_f32 v[190:191], v[190:191], v[190:191]
	v_add_f32_e32 v65, v188, v189
	v_add_f32_e32 v65, v191, v65
	v_add_f32_e32 v65, v190, v65
	s_nop 1
	v_add_f32_dpp v65, v65, v65 quad_perm:[1,0,3,2] row_mask:0xf bank_mask:0xf
	v_mov_b32_e32 v188, v33
	v_mov_b32_e32 v189, v29
	s_nop 1
	v_add_f32_dpp v65, v65, v65 quad_perm:[2,3,0,1] row_mask:0xf bank_mask:0xf
	s_nop 1
	v_add_f32_dpp v65, v65, v65 row_half_mirror row_mask:0xf bank_mask:0xf
	s_nop 1
	v_add_f32_dpp v65, v65, v65 row_mirror row_mask:0xf bank_mask:0xf
	v_fmamk_f32 v65, v65, 0x3c800000, v113
	v_mul_f32_e32 v71, 0x4b800000, v65
	v_cmp_gt_f32_e32 vcc, s45, v65
	s_nop 1
	v_cndmask_b32_e32 v65, v65, v71, vcc
	v_rsq_f32_e32 v65, v65
	s_nop 0
	v_mul_f32_e32 v71, 0x45800000, v65
	v_cndmask_b32_e32 v100, v65, v71, vcc
	v_pk_mul_f32 v[186:187], v[186:187], v[100:101] op_sel_hi:[1,0]
	v_pk_mul_f32 v[188:189], v[188:189], v[100:101] op_sel_hi:[1,0]
	v_pk_mul_f32 v[186:187], v[66:67], v[186:187]
	v_pk_mul_f32 v[188:189], v[68:69], v[188:189]
	s_branch .LBB0_370

.LBB0_370:
	v_mul_f32_e32 v65, v185, v188
	v_mul_f32_e32 v79, v183, v189
	v_fma_f32 v65, v184, v186, -v65
	v_fma_f32 v79, v182, v187, -v79
	v_mul_f32_e32 v71, s51, v65
	v_mul_f32_e32 v65, v185, v186
	v_mul_f32_e32 v89, s51, v79
	v_mul_f32_e32 v79, v183, v187
	v_fmac_f32_e32 v65, v184, v188
	v_fmac_f32_e32 v79, v182, v189
	v_mul_f32_e32 v65, s51, v65
	v_mul_f32_e32 v79, s51, v79
	s_and_b64 vcc, exec, s[6:7]
	s_mov_b64 s[8:9], -1
	s_cbranch_vccnz .LBB0_374
	v_ashrrev_i32_e32 v181, 31, v180
	v_lshlrev_b64 v[182:183], 7, v[180:181]
	v_lshl_add_u64 v[182:183], v[76:77], 0, v[182:183]
	v_cvt_pk_bf16_f32 v85, v71, v101
	global_store_short v[182:183], v85, off
	v_cvt_pk_bf16_f32 v85, v89, v101
	global_store_short v[182:183], v85, off offset:32
	v_cvt_pk_bf16_f32 v85, v65, v101
	global_store_short v[182:183], v85, off offset:64
	v_cvt_pk_bf16_f32 v85, v79, v101
	global_store_short v[182:183], v85, off offset:96
	s_cbranch_execz .LBB0_375

.LBB0_373:
	v_and_b32_e32 v79, 64, v121
	v_pk_mul_f32 v[182:183], v[180:181], v[180:181]
	v_mov_b32_e32 v184, v30
	v_mov_b32_e32 v185, v34
	v_add_u32_e32 v79, 64, v79
	v_pk_mul_f32 v[184:185], v[184:185], v[184:185]
	v_add_f32_e32 v65, v182, v183
	v_add_f32_e32 v65, v185, v65
	v_add_f32_e32 v65, v184, v65
	s_nop 1
	v_add_f32_dpp v65, v65, v65 quad_perm:[1,0,3,2] row_mask:0xf bank_mask:0xf
	v_mov_b32_e32 v182, v34
	v_mov_b32_e32 v183, v30
	s_nop 1
	v_add_f32_dpp v65, v65, v65 quad_perm:[2,3,0,1] row_mask:0xf bank_mask:0xf
	s_nop 1
	v_add_f32_dpp v65, v65, v65 row_half_mirror row_mask:0xf bank_mask:0xf
	s_nop 1
	v_add_f32_dpp v65, v65, v65 row_mirror row_mask:0xf bank_mask:0xf
	v_fmamk_f32 v65, v65, 0x3c800000, v113
	v_mul_f32_e32 v71, 0x4b800000, v65
	v_cmp_gt_f32_e32 vcc, s45, v65
	s_nop 1
	v_cndmask_b32_e32 v65, v65, v71, vcc
	v_rsq_f32_e32 v65, v65
	s_nop 0
	v_mul_f32_e32 v71, 0x45800000, v65
	v_cndmask_b32_e32 v100, v65, v71, vcc
	v_pk_mul_f32 v[180:181], v[180:181], v[100:101] op_sel_hi:[1,0]
	v_pk_mul_f32 v[182:183], v[182:183], v[100:101] op_sel_hi:[1,0]
	v_pk_mul_f32 v[180:181], v[66:67], v[180:181]
	v_pk_mul_f32 v[182:183], v[68:69], v[182:183]
	s_branch .LBB0_377

.LBB0_377:
	v_mul_f32_e32 v65, v179, v182
	v_mul_f32_e32 v79, v177, v183
	v_fma_f32 v65, v178, v180, -v65
	v_fma_f32 v79, v176, v181, -v79
	v_mul_f32_e32 v71, s51, v65
	v_mul_f32_e32 v65, v179, v180
	v_mul_f32_e32 v89, s51, v79
	v_mul_f32_e32 v79, v177, v181
	v_fmac_f32_e32 v65, v178, v182
	v_fmac_f32_e32 v79, v176, v183
	v_mul_f32_e32 v65, s51, v65
	v_mul_f32_e32 v79, s51, v79
	s_and_b64 vcc, exec, s[6:7]
	s_mov_b64 s[8:9], -1
	s_cbranch_vccnz .LBB0_381
	v_ashrrev_i32_e32 v175, 31, v174
	v_lshlrev_b64 v[176:177], 7, v[174:175]
	v_lshl_add_u64 v[176:177], v[76:77], 0, v[176:177]
	v_cvt_pk_bf16_f32 v85, v71, v101
	global_store_short v[176:177], v85, off
	v_cvt_pk_bf16_f32 v85, v89, v101
	global_store_short v[176:177], v85, off offset:32
	v_cvt_pk_bf16_f32 v85, v65, v101
	global_store_short v[176:177], v85, off offset:64
	v_cvt_pk_bf16_f32 v85, v79, v101
	global_store_short v[176:177], v85, off offset:96
	s_cbranch_execz .LBB0_382

.LBB0_380:
	v_mov_b32_e32 v100, v35
	v_and_b32_e32 v79, 64, v121
	v_pk_mul_f32 v[176:177], v[174:175], v[174:175]
	v_pk_mov_b32 v[178:179], v[30:31], v[100:101] op_sel:[1,0]
	v_add_u32_e32 v79, 64, v79
	v_pk_mul_f32 v[178:179], v[178:179], v[178:179]
	v_add_f32_e32 v65, v176, v177
	v_add_f32_e32 v65, v179, v65
	v_add_f32_e32 v65, v178, v65
	s_nop 1
	v_add_f32_dpp v65, v65, v65 quad_perm:[1,0,3,2] row_mask:0xf bank_mask:0xf
	v_mov_b32_e32 v176, v35
	v_mov_b32_e32 v177, v31
	s_nop 1
	v_add_f32_dpp v65, v65, v65 quad_perm:[2,3,0,1] row_mask:0xf bank_mask:0xf
	s_nop 1
	v_add_f32_dpp v65, v65, v65 row_half_mirror row_mask:0xf bank_mask:0xf
	s_nop 1
	v_add_f32_dpp v65, v65, v65 row_mirror row_mask:0xf bank_mask:0xf
	v_fmamk_f32 v65, v65, 0x3c800000, v113
	v_mul_f32_e32 v71, 0x4b800000, v65
	v_cmp_gt_f32_e32 vcc, s45, v65
	s_nop 1
	v_cndmask_b32_e32 v65, v65, v71, vcc
	v_rsq_f32_e32 v65, v65
	s_nop 0
	v_mul_f32_e32 v71, 0x45800000, v65
	v_cndmask_b32_e32 v100, v65, v71, vcc
	v_pk_mul_f32 v[174:175], v[174:175], v[100:101] op_sel_hi:[1,0]
	v_pk_mul_f32 v[176:177], v[176:177], v[100:101] op_sel_hi:[1,0]
	v_pk_mul_f32 v[174:175], v[66:67], v[174:175]
	v_pk_mul_f32 v[176:177], v[68:69], v[176:177]
	s_branch .LBB0_384

.LBB0_384:
	v_mul_f32_e32 v65, v173, v176
	v_mul_f32_e32 v79, v171, v177
	v_fma_f32 v65, v172, v174, -v65
	v_fma_f32 v79, v170, v175, -v79
	v_mul_f32_e32 v71, s51, v65
	v_mul_f32_e32 v65, v173, v174
	v_mul_f32_e32 v89, s51, v79
	v_mul_f32_e32 v79, v171, v175
	v_fmac_f32_e32 v65, v172, v176
	v_fmac_f32_e32 v79, v170, v177
	v_mul_f32_e32 v65, s51, v65
	v_mul_f32_e32 v79, s51, v79
	s_and_b64 vcc, exec, s[6:7]
	s_mov_b64 s[8:9], -1
	s_cbranch_vccnz .LBB0_388
	v_ashrrev_i32_e32 v169, 31, v168
	v_lshlrev_b64 v[170:171], 7, v[168:169]
	v_lshl_add_u64 v[170:171], v[76:77], 0, v[170:171]
	v_cvt_pk_bf16_f32 v85, v71, v101
	global_store_short v[170:171], v85, off
	v_cvt_pk_bf16_f32 v85, v89, v101
	global_store_short v[170:171], v85, off offset:32
	v_cvt_pk_bf16_f32 v85, v65, v101
	global_store_short v[170:171], v85, off offset:64
	v_cvt_pk_bf16_f32 v85, v79, v101
	global_store_short v[170:171], v85, off offset:96
	s_cbranch_execz .LBB0_389

.LBB0_387:
	v_and_b32_e32 v79, 64, v121
	v_pk_mul_f32 v[170:171], v[168:169], v[168:169]
	v_mov_b32_e32 v172, v12
	v_mov_b32_e32 v173, v16
	v_add_u32_e32 v79, 64, v79
	v_pk_mul_f32 v[172:173], v[172:173], v[172:173]
	v_add_f32_e32 v65, v170, v171
	v_add_f32_e32 v65, v173, v65
	v_add_f32_e32 v65, v172, v65
	s_nop 1
	v_add_f32_dpp v65, v65, v65 quad_perm:[1,0,3,2] row_mask:0xf bank_mask:0xf
	v_mov_b32_e32 v170, v16
	v_mov_b32_e32 v171, v12
	s_nop 1
	v_add_f32_dpp v65, v65, v65 quad_perm:[2,3,0,1] row_mask:0xf bank_mask:0xf
	s_nop 1
	v_add_f32_dpp v65, v65, v65 row_half_mirror row_mask:0xf bank_mask:0xf
	s_nop 1
	v_add_f32_dpp v65, v65, v65 row_mirror row_mask:0xf bank_mask:0xf
	v_fmamk_f32 v65, v65, 0x3c800000, v113
	v_mul_f32_e32 v71, 0x4b800000, v65
	v_cmp_gt_f32_e32 vcc, s45, v65
	s_nop 1
	v_cndmask_b32_e32 v65, v65, v71, vcc
	v_rsq_f32_e32 v65, v65
	s_nop 0
	v_mul_f32_e32 v71, 0x45800000, v65
	v_cndmask_b32_e32 v100, v65, v71, vcc
	v_pk_mul_f32 v[168:169], v[168:169], v[100:101] op_sel_hi:[1,0]
	v_pk_mul_f32 v[170:171], v[170:171], v[100:101] op_sel_hi:[1,0]
	v_pk_mul_f32 v[168:169], v[66:67], v[168:169]
	v_pk_mul_f32 v[170:171], v[68:69], v[170:171]
	s_branch .LBB0_391

.LBB0_391:
	v_mul_f32_e32 v65, v167, v170
	v_mul_f32_e32 v79, v165, v171
	v_fma_f32 v65, v166, v168, -v65
	v_fma_f32 v79, v164, v169, -v79
	v_mul_f32_e32 v71, s51, v65
	v_mul_f32_e32 v65, v167, v168
	v_mul_f32_e32 v85, s51, v79
	v_mul_f32_e32 v79, v165, v169
	v_fmac_f32_e32 v65, v166, v170
	v_fmac_f32_e32 v79, v164, v171
	v_mul_f32_e32 v65, s51, v65
	v_mul_f32_e32 v79, s51, v79
	s_and_b64 vcc, exec, s[6:7]
	s_mov_b64 s[8:9], -1
	s_cbranch_vccnz .LBB0_395
	v_ashrrev_i32_e32 v163, 31, v162
	v_lshlrev_b64 v[164:165], 7, v[162:163]
	v_lshl_add_u64 v[164:165], v[76:77], 0, v[164:165]
	v_cvt_pk_bf16_f32 v87, v71, v101
	global_store_short v[164:165], v87, off
	v_cvt_pk_bf16_f32 v87, v85, v101
	global_store_short v[164:165], v87, off offset:32
	v_cvt_pk_bf16_f32 v87, v65, v101
	global_store_short v[164:165], v87, off offset:64
	v_cvt_pk_bf16_f32 v87, v79, v101
	global_store_short v[164:165], v87, off offset:96
	s_cbranch_execz .LBB0_396

.LBB0_394:
	v_mov_b32_e32 v100, v17
	v_and_b32_e32 v79, 64, v121
	v_pk_mul_f32 v[164:165], v[162:163], v[162:163]
	v_pk_mov_b32 v[166:167], v[12:13], v[100:101] op_sel:[1,0]
	v_add_u32_e32 v79, 64, v79
	v_pk_mul_f32 v[166:167], v[166:167], v[166:167]
	v_add_f32_e32 v65, v164, v165
	v_add_f32_e32 v65, v167, v65
	v_add_f32_e32 v65, v166, v65
	s_nop 1
	v_add_f32_dpp v65, v65, v65 quad_perm:[1,0,3,2] row_mask:0xf bank_mask:0xf
	v_mov_b32_e32 v164, v17
	v_mov_b32_e32 v165, v13
	s_nop 1
	v_add_f32_dpp v65, v65, v65 quad_perm:[2,3,0,1] row_mask:0xf bank_mask:0xf
	s_nop 1
	v_add_f32_dpp v65, v65, v65 row_half_mirror row_mask:0xf bank_mask:0xf
	s_nop 1
	v_add_f32_dpp v65, v65, v65 row_mirror row_mask:0xf bank_mask:0xf
	v_fmamk_f32 v65, v65, 0x3c800000, v113
	v_mul_f32_e32 v71, 0x4b800000, v65
	v_cmp_gt_f32_e32 vcc, s45, v65
	s_nop 1
	v_cndmask_b32_e32 v65, v65, v71, vcc
	v_rsq_f32_e32 v65, v65
	s_nop 0
	v_mul_f32_e32 v71, 0x45800000, v65
	v_cndmask_b32_e32 v100, v65, v71, vcc
	v_pk_mul_f32 v[162:163], v[162:163], v[100:101] op_sel_hi:[1,0]
	v_pk_mul_f32 v[164:165], v[164:165], v[100:101] op_sel_hi:[1,0]
	v_pk_mul_f32 v[162:163], v[66:67], v[162:163]
	v_pk_mul_f32 v[164:165], v[68:69], v[164:165]
	s_branch .LBB0_398

.LBB0_398:
	v_mul_f32_e32 v65, v161, v164
	v_mul_f32_e32 v79, v159, v165
	v_fma_f32 v65, v160, v162, -v65
	v_fma_f32 v79, v158, v163, -v79
	v_mul_f32_e32 v71, s51, v65
	v_mul_f32_e32 v65, v161, v162
	v_mul_f32_e32 v89, s51, v79
	v_mul_f32_e32 v79, v159, v163
	v_fmac_f32_e32 v65, v160, v164
	v_fmac_f32_e32 v79, v158, v165
	v_mul_f32_e32 v65, s51, v65
	v_mul_f32_e32 v79, s51, v79
	s_and_b64 vcc, exec, s[6:7]
	s_mov_b64 s[8:9], -1
	s_cbranch_vccnz .LBB0_402
	v_ashrrev_i32_e32 v157, 31, v156
	v_lshlrev_b64 v[158:159], 7, v[156:157]
	v_lshl_add_u64 v[158:159], v[76:77], 0, v[158:159]
	v_cvt_pk_bf16_f32 v85, v71, v101
	global_store_short v[158:159], v85, off
	v_cvt_pk_bf16_f32 v85, v89, v101
	global_store_short v[158:159], v85, off offset:32
	v_cvt_pk_bf16_f32 v85, v65, v101
	global_store_short v[158:159], v85, off offset:64
	v_cvt_pk_bf16_f32 v85, v79, v101
	global_store_short v[158:159], v85, off offset:96
	s_cbranch_execz .LBB0_403

.LBB0_401:
	v_and_b32_e32 v79, 64, v121
	v_pk_mul_f32 v[158:159], v[156:157], v[156:157]
	v_mov_b32_e32 v160, v14
	v_mov_b32_e32 v161, v18
	v_add_u32_e32 v79, 64, v79
	v_pk_mul_f32 v[160:161], v[160:161], v[160:161]
	v_add_f32_e32 v65, v158, v159
	v_add_f32_e32 v65, v161, v65
	v_add_f32_e32 v65, v160, v65
	s_nop 1
	v_add_f32_dpp v65, v65, v65 quad_perm:[1,0,3,2] row_mask:0xf bank_mask:0xf
	v_mov_b32_e32 v158, v18
	v_mov_b32_e32 v159, v14
	s_nop 1
	v_add_f32_dpp v65, v65, v65 quad_perm:[2,3,0,1] row_mask:0xf bank_mask:0xf
	s_nop 1
	v_add_f32_dpp v65, v65, v65 row_half_mirror row_mask:0xf bank_mask:0xf
	s_nop 1
	v_add_f32_dpp v65, v65, v65 row_mirror row_mask:0xf bank_mask:0xf
	v_fmamk_f32 v65, v65, 0x3c800000, v113
	v_mul_f32_e32 v71, 0x4b800000, v65
	v_cmp_gt_f32_e32 vcc, s45, v65
	s_nop 1
	v_cndmask_b32_e32 v65, v65, v71, vcc
	v_rsq_f32_e32 v65, v65
	s_nop 0
	v_mul_f32_e32 v71, 0x45800000, v65
	v_cndmask_b32_e32 v100, v65, v71, vcc
	v_pk_mul_f32 v[156:157], v[156:157], v[100:101] op_sel_hi:[1,0]
	v_pk_mul_f32 v[158:159], v[158:159], v[100:101] op_sel_hi:[1,0]
	v_pk_mul_f32 v[156:157], v[66:67], v[156:157]
	v_pk_mul_f32 v[158:159], v[68:69], v[158:159]
	s_branch .LBB0_405

.LBB0_405:
	v_mul_f32_e32 v65, v155, v158
	v_mul_f32_e32 v79, v153, v159
	v_fma_f32 v65, v154, v156, -v65
	v_fma_f32 v79, v152, v157, -v79
	v_mul_f32_e32 v71, s51, v65
	v_mul_f32_e32 v65, v155, v156
	v_mul_f32_e32 v89, s51, v79
	v_mul_f32_e32 v79, v153, v157
	v_fmac_f32_e32 v65, v154, v158
	v_fmac_f32_e32 v79, v152, v159
	v_mul_f32_e32 v65, s51, v65
	v_mul_f32_e32 v79, s51, v79
	s_and_b64 vcc, exec, s[6:7]
	s_mov_b64 s[8:9], -1
	s_cbranch_vccnz .LBB0_409
	v_ashrrev_i32_e32 v151, 31, v150
	v_lshlrev_b64 v[152:153], 7, v[150:151]
	v_lshl_add_u64 v[152:153], v[76:77], 0, v[152:153]
	v_cvt_pk_bf16_f32 v85, v71, v101
	global_store_short v[152:153], v85, off
	v_cvt_pk_bf16_f32 v85, v89, v101
	global_store_short v[152:153], v85, off offset:32
	v_cvt_pk_bf16_f32 v85, v65, v101
	global_store_short v[152:153], v85, off offset:64
	v_cvt_pk_bf16_f32 v85, v79, v101
	global_store_short v[152:153], v85, off offset:96
	s_cbranch_execz .LBB0_410

.LBB0_408:
	v_mov_b32_e32 v100, v19
	v_and_b32_e32 v79, 64, v121
	v_pk_mul_f32 v[152:153], v[150:151], v[150:151]
	v_pk_mov_b32 v[154:155], v[14:15], v[100:101] op_sel:[1,0]
	v_add_u32_e32 v79, 64, v79
	v_pk_mul_f32 v[154:155], v[154:155], v[154:155]
	v_add_f32_e32 v65, v152, v153
	v_add_f32_e32 v65, v155, v65
	v_add_f32_e32 v65, v154, v65
	s_nop 1
	v_add_f32_dpp v65, v65, v65 quad_perm:[1,0,3,2] row_mask:0xf bank_mask:0xf
	v_mov_b32_e32 v152, v19
	v_mov_b32_e32 v153, v15
	s_nop 1
	v_add_f32_dpp v65, v65, v65 quad_perm:[2,3,0,1] row_mask:0xf bank_mask:0xf
	s_nop 1
	v_add_f32_dpp v65, v65, v65 row_half_mirror row_mask:0xf bank_mask:0xf
	s_nop 1
	v_add_f32_dpp v65, v65, v65 row_mirror row_mask:0xf bank_mask:0xf
	v_fmamk_f32 v65, v65, 0x3c800000, v113
	v_mul_f32_e32 v71, 0x4b800000, v65
	v_cmp_gt_f32_e32 vcc, s45, v65
	s_nop 1
	v_cndmask_b32_e32 v65, v65, v71, vcc
	v_rsq_f32_e32 v65, v65
	s_nop 0
	v_mul_f32_e32 v71, 0x45800000, v65
	v_cndmask_b32_e32 v100, v65, v71, vcc
	v_pk_mul_f32 v[150:151], v[150:151], v[100:101] op_sel_hi:[1,0]
	v_pk_mul_f32 v[152:153], v[152:153], v[100:101] op_sel_hi:[1,0]
	v_pk_mul_f32 v[150:151], v[66:67], v[150:151]
	v_pk_mul_f32 v[152:153], v[68:69], v[152:153]
	s_branch .LBB0_412

.LBB0_412:
	v_mul_f32_e32 v65, v149, v152
	v_mul_f32_e32 v79, v147, v153
	v_fma_f32 v65, v148, v150, -v65
	v_fma_f32 v79, v146, v151, -v79
	v_mul_f32_e32 v71, s51, v65
	v_mul_f32_e32 v65, v149, v150
	v_mul_f32_e32 v89, s51, v79
	v_mul_f32_e32 v79, v147, v151
	v_fmac_f32_e32 v65, v148, v152
	v_fmac_f32_e32 v79, v146, v153
	v_mul_f32_e32 v65, s51, v65
	v_mul_f32_e32 v79, s51, v79
	s_and_b64 vcc, exec, s[6:7]
	s_mov_b64 s[8:9], -1
	s_cbranch_vccnz .LBB0_416
	v_ashrrev_i32_e32 v145, 31, v144
	v_lshlrev_b64 v[146:147], 7, v[144:145]
	v_lshl_add_u64 v[146:147], v[76:77], 0, v[146:147]
	v_cvt_pk_bf16_f32 v85, v71, v101
	global_store_short v[146:147], v85, off
	v_cvt_pk_bf16_f32 v85, v89, v101
	global_store_short v[146:147], v85, off offset:32
	v_cvt_pk_bf16_f32 v85, v65, v101
	global_store_short v[146:147], v85, off offset:64
	v_cvt_pk_bf16_f32 v85, v79, v101
	global_store_short v[146:147], v85, off offset:96
	s_cbranch_execz .LBB0_417

.LBB0_415:
	v_and_b32_e32 v79, 64, v121
	v_pk_mul_f32 v[146:147], v[144:145], v[144:145]
	v_mov_b32_e32 v148, v48
	v_mov_b32_e32 v149, v0
	v_add_u32_e32 v79, 64, v79
	v_pk_mul_f32 v[148:149], v[148:149], v[148:149]
	v_add_f32_e32 v65, v146, v147
	v_add_f32_e32 v65, v149, v65
	v_add_f32_e32 v65, v148, v65
	s_nop 1
	v_add_f32_dpp v65, v65, v65 quad_perm:[1,0,3,2] row_mask:0xf bank_mask:0xf
	v_mov_b32_e32 v146, v0
	v_mov_b32_e32 v147, v48
	s_nop 1
	v_add_f32_dpp v65, v65, v65 quad_perm:[2,3,0,1] row_mask:0xf bank_mask:0xf
	s_nop 1
	v_add_f32_dpp v65, v65, v65 row_half_mirror row_mask:0xf bank_mask:0xf
	s_nop 1
	v_add_f32_dpp v65, v65, v65 row_mirror row_mask:0xf bank_mask:0xf
	v_fmamk_f32 v65, v65, 0x3c800000, v113
	v_mul_f32_e32 v71, 0x4b800000, v65
	v_cmp_gt_f32_e32 vcc, s45, v65
	s_nop 1
	v_cndmask_b32_e32 v65, v65, v71, vcc
	v_rsq_f32_e32 v65, v65
	s_nop 0
	v_mul_f32_e32 v71, 0x45800000, v65
	v_cndmask_b32_e32 v100, v65, v71, vcc
	v_pk_mul_f32 v[144:145], v[144:145], v[100:101] op_sel_hi:[1,0]
	v_pk_mul_f32 v[146:147], v[146:147], v[100:101] op_sel_hi:[1,0]
	v_pk_mul_f32 v[144:145], v[66:67], v[144:145]
	v_pk_mul_f32 v[146:147], v[68:69], v[146:147]
	s_branch .LBB0_419

.LBB0_419:
	v_mul_f32_e32 v65, v143, v146
	v_mul_f32_e32 v79, v141, v147
	v_fma_f32 v65, v142, v144, -v65
	v_fma_f32 v79, v140, v145, -v79
	v_mul_f32_e32 v71, s51, v65
	v_mul_f32_e32 v65, v143, v144
	v_mul_f32_e32 v85, s51, v79
	v_mul_f32_e32 v79, v141, v145
	v_fmac_f32_e32 v65, v142, v146
	v_fmac_f32_e32 v79, v140, v147
	v_mul_f32_e32 v65, s51, v65
	v_mul_f32_e32 v79, s51, v79
	s_and_b64 vcc, exec, s[6:7]
	s_mov_b64 s[8:9], -1
	s_cbranch_vccnz .LBB0_423
	v_ashrrev_i32_e32 v95, 31, v94
	v_lshlrev_b64 v[140:141], 7, v[94:95]
	v_lshl_add_u64 v[140:141], v[76:77], 0, v[140:141]
	v_cvt_pk_bf16_f32 v87, v71, v101
	global_store_short v[140:141], v87, off
	v_cvt_pk_bf16_f32 v87, v85, v101
	global_store_short v[140:141], v87, off offset:32
	v_cvt_pk_bf16_f32 v87, v65, v101
	global_store_short v[140:141], v87, off offset:64
	v_cvt_pk_bf16_f32 v87, v79, v101
	global_store_short v[140:141], v87, off offset:96
	s_cbranch_execz .LBB0_424

.LBB0_422:
	v_mov_b32_e32 v100, v1
	v_and_b32_e32 v79, 64, v121
	v_pk_mul_f32 v[140:141], v[94:95], v[94:95]
	v_pk_mov_b32 v[142:143], v[48:49], v[100:101] op_sel:[1,0]
	v_add_u32_e32 v79, 64, v79
	v_pk_mul_f32 v[142:143], v[142:143], v[142:143]
	v_add_f32_e32 v65, v140, v141
	v_add_f32_e32 v65, v143, v65
	v_add_f32_e32 v65, v142, v65
	s_nop 1
	v_add_f32_dpp v65, v65, v65 quad_perm:[1,0,3,2] row_mask:0xf bank_mask:0xf
	v_mov_b32_e32 v140, v1
	v_mov_b32_e32 v141, v49
	s_nop 1
	v_add_f32_dpp v65, v65, v65 quad_perm:[2,3,0,1] row_mask:0xf bank_mask:0xf
	s_nop 1
	v_add_f32_dpp v65, v65, v65 row_half_mirror row_mask:0xf bank_mask:0xf
	s_nop 1
	v_add_f32_dpp v65, v65, v65 row_mirror row_mask:0xf bank_mask:0xf
	v_fmamk_f32 v65, v65, 0x3c800000, v113
	v_mul_f32_e32 v71, 0x4b800000, v65
	v_cmp_gt_f32_e32 vcc, s45, v65
	s_nop 1
	v_cndmask_b32_e32 v65, v65, v71, vcc
	v_rsq_f32_e32 v65, v65
	s_nop 0
	v_mul_f32_e32 v71, 0x45800000, v65
	v_cndmask_b32_e32 v100, v65, v71, vcc
	v_pk_mul_f32 v[94:95], v[94:95], v[100:101] op_sel_hi:[1,0]
	v_pk_mul_f32 v[140:141], v[140:141], v[100:101] op_sel_hi:[1,0]
	v_pk_mul_f32 v[94:95], v[66:67], v[94:95]
	v_pk_mul_f32 v[140:141], v[68:69], v[140:141]
	s_branch .LBB0_426

.LBB0_426:
	v_mul_f32_e32 v65, v93, v140
	v_fma_f32 v65, v92, v94, -v65
	v_mul_f32_e32 v79, v91, v141
	v_mul_f32_e32 v71, s51, v65
	v_mul_f32_e32 v65, v93, v94
	v_fma_f32 v79, v90, v95, -v79
	v_fmac_f32_e32 v65, v92, v140
	v_mul_f32_e32 v92, s51, v79
	v_mul_f32_e32 v79, v91, v95
	v_fmac_f32_e32 v79, v90, v141
	v_mul_f32_e32 v65, s51, v65
	v_mul_f32_e32 v79, s51, v79
	s_and_b64 vcc, exec, s[6:7]
	s_mov_b64 s[8:9], -1
	s_cbranch_vccnz .LBB0_430
	v_ashrrev_i32_e32 v89, 31, v88
	v_lshlrev_b64 v[90:91], 7, v[88:89]
	v_lshl_add_u64 v[90:91], v[76:77], 0, v[90:91]
	v_cvt_pk_bf16_f32 v85, v71, v101
	global_store_short v[90:91], v85, off
	v_cvt_pk_bf16_f32 v85, v92, v101
	global_store_short v[90:91], v85, off offset:32
	v_cvt_pk_bf16_f32 v85, v65, v101
	global_store_short v[90:91], v85, off offset:64
	v_cvt_pk_bf16_f32 v85, v79, v101
	global_store_short v[90:91], v85, off offset:96
	s_cbranch_execz .LBB0_431

.LBB0_429:
	v_and_b32_e32 v79, 64, v121
	v_pk_mul_f32 v[90:91], v[88:89], v[88:89]
	v_mov_b32_e32 v92, v50
	v_mov_b32_e32 v93, v2
	v_add_u32_e32 v79, 64, v79
	v_pk_mul_f32 v[92:93], v[92:93], v[92:93]
	v_add_f32_e32 v65, v90, v91
	v_add_f32_e32 v65, v93, v65
	v_add_f32_e32 v65, v92, v65
	s_nop 1
	v_add_f32_dpp v65, v65, v65 quad_perm:[1,0,3,2] row_mask:0xf bank_mask:0xf
	v_mov_b32_e32 v92, v2
	v_mov_b32_e32 v93, v50
	s_nop 1
	v_add_f32_dpp v65, v65, v65 quad_perm:[2,3,0,1] row_mask:0xf bank_mask:0xf
	s_nop 1
	v_add_f32_dpp v65, v65, v65 row_half_mirror row_mask:0xf bank_mask:0xf
	s_nop 1
	v_add_f32_dpp v65, v65, v65 row_mirror row_mask:0xf bank_mask:0xf
	v_fmamk_f32 v65, v65, 0x3c800000, v113
	v_mul_f32_e32 v71, 0x4b800000, v65
	v_cmp_gt_f32_e32 vcc, s45, v65
	s_nop 1
	v_cndmask_b32_e32 v65, v65, v71, vcc
	v_rsq_f32_e32 v65, v65
	s_nop 0
	v_mul_f32_e32 v71, 0x45800000, v65
	v_cndmask_b32_e32 v90, v65, v71, vcc
	v_pk_mul_f32 v[88:89], v[88:89], v[90:91] op_sel_hi:[1,0]
	v_pk_mul_f32 v[90:91], v[92:93], v[90:91] op_sel_hi:[1,0]
	v_pk_mul_f32 v[88:89], v[66:67], v[88:89]
	v_pk_mul_f32 v[90:91], v[68:69], v[90:91]
	s_branch .LBB0_433

.LBB0_433:
	v_mul_f32_e32 v65, v83, v90
	v_fma_f32 v65, v82, v88, -v65
	v_mul_f32_e32 v79, v81, v91
	v_mul_f32_e32 v71, s51, v65
	v_mul_f32_e32 v65, v83, v88
	v_fma_f32 v79, v80, v89, -v79
	v_fmac_f32_e32 v65, v82, v90
	v_mul_f32_e32 v82, s51, v79
	v_mul_f32_e32 v79, v81, v89
	v_fmac_f32_e32 v79, v80, v91
	v_mul_f32_e32 v65, s51, v65
	v_mul_f32_e32 v80, s51, v79
	s_and_b64 vcc, exec, s[6:7]
	s_mov_b64 s[8:9], -1
	s_cbranch_vccnz .LBB0_437
	v_ashrrev_i32_e32 v79, 31, v78
	v_lshlrev_b64 v[88:89], 7, v[78:79]
	v_lshl_add_u64 v[88:89], v[76:77], 0, v[88:89]
	v_cvt_pk_bf16_f32 v79, v71, v101
	global_store_short v[88:89], v79, off
	v_cvt_pk_bf16_f32 v79, v82, v101
	global_store_short v[88:89], v79, off offset:32
	v_cvt_pk_bf16_f32 v79, v65, v101
	global_store_short v[88:89], v79, off offset:64
	v_cvt_pk_bf16_f32 v79, v80, v101
	global_store_short v[88:89], v79, off offset:96
	s_cbranch_execz .LBB0_438

.LBB0_436:
	v_mov_b32_e32 v78, v11
	v_mov_b32_e32 v79, v7
	v_pk_mul_f32 v[80:81], v[78:79], v[78:79]
	v_mov_b32_e32 v82, v3
	v_add_f32_e32 v65, v80, v81
	v_and_b32_e32 v80, 64, v121
	v_pk_mov_b32 v[82:83], v[50:51], v[82:83] op_sel:[1,0]
	v_add_u32_e32 v80, 64, v80
	v_pk_mul_f32 v[82:83], v[82:83], v[82:83]
	v_cmp_lt_i32_e32 vcc, v71, v80
	v_add_f32_e32 v65, v83, v65
	v_add_f32_e32 v65, v82, v65
	s_nop 1
	v_add_f32_dpp v65, v65, v65 quad_perm:[1,0,3,2] row_mask:0xf bank_mask:0xf
	s_waitcnt lgkmcnt(0)
	v_cmp_lt_i32_e32 vcc, v71, v80
	s_nop 1
	s_nop 1
	v_add_f32_dpp v65, v65, v65 quad_perm:[2,3,0,1] row_mask:0xf bank_mask:0xf
	s_waitcnt lgkmcnt(0)
	v_cmp_lt_i32_e32 vcc, v71, v80
	s_nop 1
	s_nop 1
	v_add_f32_dpp v65, v65, v65 row_half_mirror row_mask:0xf bank_mask:0xf
	s_waitcnt lgkmcnt(0)
	v_cmp_lt_i32_e32 vcc, v71, v80
	s_nop 1
	s_nop 1
	v_add_f32_dpp v65, v65, v65 row_mirror row_mask:0xf bank_mask:0xf
	v_fmamk_f32 v65, v65, 0x3c800000, v113
	v_mul_f32_e32 v71, 0x4b800000, v65
	v_cmp_gt_f32_e32 vcc, s45, v65
	s_nop 1
	v_cndmask_b32_e32 v65, v65, v71, vcc
	v_rsq_f32_e32 v65, v65
	s_nop 0
	v_mul_f32_e32 v71, 0x45800000, v65
	v_cndmask_b32_e32 v80, v65, v71, vcc
	v_pk_mul_f32 v[78:79], v[78:79], v[80:81] op_sel_hi:[1,0]
	s_nop 0
	v_pk_mul_f32 v[66:67], v[66:67], v[78:79]
	v_mov_b32_e32 v78, v3
	v_mov_b32_e32 v79, v51
	v_pk_mul_f32 v[78:79], v[78:79], v[80:81] op_sel_hi:[1,0]
	s_nop 0
	v_pk_mul_f32 v[68:69], v[68:69], v[78:79]
	s_branch .LBB0_440

.LBB0_440:
	v_mul_f32_e32 v65, v75, v68
	v_fma_f32 v65, v74, v66, -v65
	v_mul_f32_e32 v78, s51, v65
	v_mul_f32_e32 v65, v75, v66
	v_mul_f32_e32 v66, v73, v69
	v_fma_f32 v66, v72, v67, -v66
	v_fmac_f32_e32 v65, v74, v68
	v_mul_f32_e32 v68, s51, v66
	v_mul_f32_e32 v66, v73, v67
	v_fmac_f32_e32 v66, v72, v69
	v_mul_f32_e32 v65, s51, v65
	v_mul_f32_e32 v66, s51, v66
	s_and_b64 vcc, exec, s[6:7]
	s_mov_b64 s[4:5], -1
	s_cbranch_vccnz .LBB0_442
	v_ashrrev_i32_e32 v71, 31, v70
	v_lshlrev_b64 v[72:73], 7, v[70:71]
	v_lshl_add_u64 v[72:73], v[76:77], 0, v[72:73]
	v_cvt_pk_bf16_f32 v67, v78, v101
	global_store_short v[72:73], v67, off
	v_cvt_pk_bf16_f32 v67, v68, v101
	global_store_short v[72:73], v67, off offset:32
	v_cvt_pk_bf16_f32 v67, v65, v101
	s_mov_b64 s[4:5], 0
	global_store_short v[72:73], v67, off offset:64
	v_cvt_pk_bf16_f32 v67, v66, v101
	global_store_short v[72:73], v67, off offset:96
